# conversion rebalancing: 2048 (layers 1-2) / 512 (layer 0) more next-layer items converted in the FFN-up idle half round, on top of the fixed conversion loops
# baseline (speedup 1.0000x reference)
; __device__ __forceinline__ PItem p0_decode(const Args& a, int it) {
;     constexpr int I_IN = 16 * 96, I_OUT = 16 * 32, I_W1 = 16 * 88, I_W2 = 44 * 32, I_LAYER = I_IN + I_OUT + 2 * I_W1 + I_W2;
;     const int l = it / I_LAYER, e = l >> 1, odd = l & 1; int r = it % I_LAYER;
;     unsigned char* wl = a.ws + WS_W + (size_t)l * W_LAYER; float* cv = (float*)(a.ws + WS_CVEC) + (size_t)l * CVEC_LAYER;
;     PItem p;
;     if (r < I_IN) { const int kb = r / 96, nb = r % 96; p.W = (odd ? a.in[13] : a.in[5]) + (size_t)e * D * EIN; p.N = EIN; p.K = D; p.g = l > 0 ? a.in[21] + (size_t)(l - 1) * D : nullptr; p.be = l > 0 ? a.in[22] + (size_t)(l - 1) * D : nullptr;
;         p.WT = (bf16*)(wl + W_IN); p.drow0 = in_dst_row(32 * nb, odd); p.k0 = 64 * kb; p.n0 = 32 * nb; p.c1 = cv; p.c2 = cv + EIN; return p; } r -= I_IN;
;     if (r < I_OUT) { const int kb = r / 32, nb = r % 32; p.W = (odd ? a.in[15] : a.in[6]) + (size_t)e * D * D; p.N = D; p.K = D; p.g = nullptr; p.be = nullptr;
;         p.WT = (bf16*)(wl + W_OUT); p.drow0 = 32 * nb; p.k0 = 64 * kb; p.n0 = 32 * nb; p.c1 = nullptr; p.c2 = nullptr; return p; } r -= I_OUT;
;     if (r < 2 * I_W1) { const int second = r >= I_W1; if (second) r -= I_W1; const int kb = r / 88, nb = r % 88, n0 = 32 * nb; p.W = (second ? a.in[17] : a.in[16]) + (size_t)l * D * DFF; p.N = DFF; p.K = D;
;         p.g = a.in[19] + (size_t)l * D; p.be = a.in[20] + (size_t)l * D; p.WT = (bf16*)(wl + W_13); p.drow0 = 256 * (n0 >> 7) + (second ? 128 : 0) + (n0 & 127); p.k0 = 64 * kb; p.n0 = n0; p.c1 = cv + 2 * EIN; p.c2 = cv + 2 * EIN + NUP; return p; } r -= 2 * I_W1;
; __global__ void __launch_bounds__(NWAVES * 64, 2) mk_fwd(Args args) {
;     ...
;             if (F.G == 256 && (int)blockIdx.x >= 128) { const int wi = (int)blockIdx.x - 128;
;                 if (l == 0) p_convert_tail(F, args, P_ILAYER - P_IW2, P_ILAYER, wi, 128);
;                 if (l < 3) { const int xs = (l == 0) ? 768 : 1792; p_convert_tail(F, args, (l + 2) * P_ILAYER - xs, (l + 2) * P_ILAYER, wi, 128); } }
.LBB0_1294:
	v_readlane_b32 s0, v255, 62
	s_cmp_eq_u32 s0, 3
	v_readlane_b32 s1, v255, 63
	s_cbranch_scc1 .LBB0_1348
	v_readlane_b32 s0, v255, 53
	v_readlane_b32 s1, v255, 54
	s_and_b64 s[0:1], s[0:1], exec
	v_readlane_b32 s10, v255, 62
	s_movk_i32 s0, 0xfb00
	s_mul_i32 s7, s10, 0x1880
	s_cselect_b32 s0, s0, 0xfffff100
	s_addk_i32 s7, 0x3100
	v_readlane_b32 s1, v253, 59
	s_add_i32 s1, s1, s7
	v_mbcnt_lo_u32_b32 v0, -1, 0
	v_mbcnt_hi_u32_b32 v0, -1, v0
	s_add_i32 s13, s1, s0
	v_add_u32_e32 v0, s75, v0
	s_cmp_ge_i32 s13, s7
	v_readlane_b32 s11, v255, 63
	s_cbranch_scc1 .LBB0_1348
	s_mul_hi_i32 s0, s13, 0x5397829d
	s_lshr_b32 s1, s0, 31
	s_ashr_i32 s0, s0, 11
	s_add_i32 s30, s0, s1
	s_mul_i32 s1, s30, 0x1880
	s_ashr_i32 s34, s30, 1
	s_and_b32 s0, s30, 1
	s_sub_i32 s1, s13, s1
	s_ashr_i32 s31, s30, 31
	s_mul_i32 s10, s30, 0x1880000
	v_readlane_b32 s11, v253, 5
	s_mul_hi_i32 s2, s30, 0x1880000
	s_add_u32 s22, s11, s10
	v_readlane_b32 s10, v253, 6
	s_addc_u32 s23, s10, s2
	s_mul_i32 s10, s30, 0x11000
	v_readlane_b32 s11, v253, 7
	s_mul_hi_i32 s2, s30, 0x11000
	s_add_u32 s26, s11, s10
	v_readlane_b32 s10, v253, 8
	s_addc_u32 s27, s10, s2
	s_cmpk_gt_i32 s1, 0x5ff
	s_mov_b64 s[48:49], -1
	s_cbranch_scc0 .LBB0_1305
	s_cmpk_gt_u32 s1, 0x7ff
	s_cbranch_scc0 .LBB0_1302
	s_mov_b64 s[18:19], -1
	s_cmpk_gt_u32 s1, 0x12ff
	s_mul_hi_i32 s2, s30, 0xb00000
	s_mul_i32 s17, s30, 0xb00000
	s_cbranch_scc0 .LBB0_1300
	v_readlane_b32 s56, v253, 26
	v_readlane_b32 s57, v253, 27
	s_add_u32 s10, s56, s17
	s_addc_u32 s11, s57, s2
	s_add_u32 s14, s22, 0x1300000
	s_addc_u32 s15, s23, 0
	s_lshl_b32 s16, s1, 1
	s_lshl_b32 s12, s1, 5
	s_and_b32 s16, s16, 0x7fffffc0
	v_readlane_b32 s58, v253, 28
	v_readlane_b32 s59, v253, 29
	v_readlane_b32 s60, v253, 30
	v_readlane_b32 s61, v253, 31
	v_readlane_b32 s62, v253, 32
	v_readlane_b32 s63, v253, 33
	s_and_b32 s12, s12, 0x3e0
	s_addk_i32 s16, 0xda00
	s_mov_b64 s[18:19], 0

; __device__ __forceinline__ PItem p0_decode(const Args& a, int it) {
;     constexpr int I_IN = 16 * 96, I_OUT = 16 * 32, I_W1 = 16 * 88, I_W2 = 44 * 32, I_LAYER = I_IN + I_OUT + 2 * I_W1 + I_W2;
;     const int l = it / I_LAYER, e = l >> 1, odd = l & 1; int r = it % I_LAYER;
;     unsigned char* wl = a.ws + WS_W + (size_t)l * W_LAYER; float* cv = (float*)(a.ws + WS_CVEC) + (size_t)l * CVEC_LAYER;
;     PItem p;
;     if (r < I_IN) { const int kb = r / 96, nb = r % 96; p.W = (odd ? a.in[13] : a.in[5]) + (size_t)e * D * EIN; p.N = EIN; p.K = D; p.g = l > 0 ? a.in[21] + (size_t)(l - 1) * D : nullptr; p.be = l > 0 ? a.in[22] + (size_t)(l - 1) * D : nullptr;
;         p.WT = (bf16*)(wl + W_IN); p.drow0 = in_dst_row(32 * nb, odd); p.k0 = 64 * kb; p.n0 = 32 * nb; p.c1 = cv; p.c2 = cv + EIN; return p; } r -= I_IN;
;     if (r < I_OUT) { const int kb = r / 32, nb = r % 32; p.W = (odd ? a.in[15] : a.in[6]) + (size_t)e * D * D; p.N = D; p.K = D; p.g = nullptr; p.be = nullptr;
;         p.WT = (bf16*)(wl + W_OUT); p.drow0 = 32 * nb; p.k0 = 64 * kb; p.n0 = 32 * nb; p.c1 = nullptr; p.c2 = nullptr; return p; } r -= I_OUT;
;     if (r < 2 * I_W1) { const int second = r >= I_W1; if (second) r -= I_W1; const int kb = r / 88, nb = r % 88, n0 = 32 * nb; p.W = (second ? a.in[17] : a.in[16]) + (size_t)l * D * DFF; p.N = DFF; p.K = D;
;         p.g = a.in[19] + (size_t)l * D; p.be = a.in[20] + (size_t)l * D; p.WT = (bf16*)(wl + W_13); p.drow0 = 256 * (n0 >> 7) + (second ? 128 : 0) + (n0 & 127); p.k0 = 64 * kb; p.n0 = n0; p.c1 = cv + 2 * EIN; p.c2 = cv + 2 * EIN + NUP; return p; } r -= 2 * I_W1;
; __global__ void __launch_bounds__(NWAVES * 64, 2) mk_fwd(Args args) {
;     ...
;                   if (l < 3) { if (mfirst > 0) { if ((int)blockIdx.x < mfirst) { p_convert_tail(F, args, (l + 1) * P_ILAYER, (l + 2) * P_ILAYER - ((F.G == 256) ? (l == 0 ? 768 : 1792) : 0), (int)blockIdx.x, mfirst); if (l == 0) p_state_copies_tail(F, args, (int)blockIdx.x, mfirst); } }
;                   else { p_convert_tail(F, args, (l + 1) * P_ILAYER, (l + 2) * P_ILAYER - ((F.G == 256) ? (l == 0 ? 768 : 1792) : 0), (int)blockIdx.x, F.G); if (l == 0) p_state_copies_tail(F, args, (int)blockIdx.x, F.G); } } } }
.LBB0_1546:
	s_waitcnt vmcnt(0)
	s_barrier
	v_readlane_b32 s0, v255, 62
	s_cmp_lg_u32 s0, 3
	s_mov_b64 s[10:11], -1
	v_readlane_b32 s1, v255, 63
	s_cbranch_scc0 .LBB0_1764
	s_cmp_lt_i32 s29, 33
	s_cbranch_scc0 .LBB0_1627
	v_readlane_b32 s0, v255, 62
	v_readlane_b32 s1, v255, 63
	s_mul_i32 s2, s0, 0x1880
	v_readlane_b32 s0, v255, 53
	v_readlane_b32 s1, v255, 54
	s_and_b64 s[0:1], s[0:1], exec
	s_movk_i32 s0, 0xfb00
	s_cselect_b32 s7, s0, 0xfffff100
	v_readlane_b32 s0, v252, 62
	v_readlane_b32 s1, v252, 63
	s_and_b64 s[0:1], s[0:1], exec
	s_cselect_b32 s0, s7, 0
	s_add_i32 s7, s2, s0
	v_readlane_b32 s0, v253, 60
	s_addk_i32 s7, 0x3100
	v_mbcnt_lo_u32_b32 v0, -1, 0
	v_mbcnt_hi_u32_b32 v0, -1, v0
	s_add_i32 s29, s0, s2
	v_add_u32_e32 v0, s75, v0
	s_cmp_ge_i32 s29, s7
	s_cbranch_scc1 .LBB0_1601
	s_mul_hi_i32 s0, s29, 0x5397829d
	s_lshr_b32 s1, s0, 31
	s_ashr_i32 s0, s0, 11
	s_add_i32 s26, s0, s1
	s_mul_i32 s1, s26, 0x1880
	s_ashr_i32 s30, s26, 1
	s_and_b32 s0, s26, 1
	s_sub_i32 s1, s29, s1
	s_ashr_i32 s27, s26, 31
	s_mul_i32 s10, s26, 0x1880000
	v_readlane_b32 s11, v253, 5
	s_mul_hi_i32 s2, s26, 0x1880000
	s_add_u32 s22, s11, s10
	v_readlane_b32 s10, v253, 6
	s_addc_u32 s23, s10, s2
	s_mul_i32 s10, s26, 0x11000
	v_readlane_b32 s11, v253, 7
	s_mul_hi_i32 s2, s26, 0x11000
	s_add_u32 s24, s11, s10
	v_readlane_b32 s10, v253, 8
	s_addc_u32 s25, s10, s2
	s_cmpk_gt_i32 s1, 0x5ff
	s_mov_b64 s[46:47], -1
	s_cbranch_scc0 .LBB0_1558
	s_cmpk_gt_u32 s1, 0x7ff
	s_cbranch_scc0 .LBB0_1555
	s_mov_b64 s[18:19], -1
	s_cmpk_gt_u32 s1, 0x12ff
	s_mul_hi_i32 s2, s26, 0xb00000
	s_mul_i32 s13, s26, 0xb00000
	s_cbranch_scc0 .LBB0_1553
	v_readlane_b32 s56, v253, 26
	v_readlane_b32 s57, v253, 27
	s_add_u32 s10, s56, s13
	s_addc_u32 s11, s57, s2
	s_add_u32 s14, s22, 0x1300000
	s_addc_u32 s15, s23, 0
	s_lshl_b32 s16, s1, 1
	s_lshl_b32 s12, s1, 5
	s_and_b32 s16, s16, 0x7fffffc0
	v_readlane_b32 s58, v253, 28
	v_readlane_b32 s59, v253, 29
	v_readlane_b32 s60, v253, 30
	v_readlane_b32 s61, v253, 31
	v_readlane_b32 s62, v253, 32
	v_readlane_b32 s63, v253, 33
	s_and_b32 s12, s12, 0x3e0
	s_addk_i32 s16, 0xda00
	s_mov_b64 s[18:19], 0

; __device__ __forceinline__ PItem p0_decode(const Args& a, int it) {
;     constexpr int I_IN = 16 * 96, I_OUT = 16 * 32, I_W1 = 16 * 88, I_W2 = 44 * 32, I_LAYER = I_IN + I_OUT + 2 * I_W1 + I_W2;
;     const int l = it / I_LAYER, e = l >> 1, odd = l & 1; int r = it % I_LAYER;
;     unsigned char* wl = a.ws + WS_W + (size_t)l * W_LAYER; float* cv = (float*)(a.ws + WS_CVEC) + (size_t)l * CVEC_LAYER;
;     PItem p;
;     if (r < I_IN) { const int kb = r / 96, nb = r % 96; p.W = (odd ? a.in[13] : a.in[5]) + (size_t)e * D * EIN; p.N = EIN; p.K = D; p.g = l > 0 ? a.in[21] + (size_t)(l - 1) * D : nullptr; p.be = l > 0 ? a.in[22] + (size_t)(l - 1) * D : nullptr;
;         p.WT = (bf16*)(wl + W_IN); p.drow0 = in_dst_row(32 * nb, odd); p.k0 = 64 * kb; p.n0 = 32 * nb; p.c1 = cv; p.c2 = cv + EIN; return p; } r -= I_IN;
;     if (r < I_OUT) { const int kb = r / 32, nb = r % 32; p.W = (odd ? a.in[15] : a.in[6]) + (size_t)e * D * D; p.N = D; p.K = D; p.g = nullptr; p.be = nullptr;
;         p.WT = (bf16*)(wl + W_OUT); p.drow0 = 32 * nb; p.k0 = 64 * kb; p.n0 = 32 * nb; p.c1 = nullptr; p.c2 = nullptr; return p; } r -= I_OUT;
;     if (r < 2 * I_W1) { const int second = r >= I_W1; if (second) r -= I_W1; const int kb = r / 88, nb = r % 88, n0 = 32 * nb; p.W = (second ? a.in[17] : a.in[16]) + (size_t)l * D * DFF; p.N = DFF; p.K = D;
;         p.g = a.in[19] + (size_t)l * D; p.be = a.in[20] + (size_t)l * D; p.WT = (bf16*)(wl + W_13); p.drow0 = 256 * (n0 >> 7) + (second ? 128 : 0) + (n0 & 127); p.k0 = 64 * kb; p.n0 = n0; p.c1 = cv + 2 * EIN; p.c2 = cv + 2 * EIN + NUP; return p; } r -= 2 * I_W1;
; __global__ void __launch_bounds__(NWAVES * 64, 2) mk_fwd(Args args) {
;     ...
;                   if (l < 3) { if (mfirst > 0) { if ((int)blockIdx.x < mfirst) { p_convert_tail(F, args, (l + 1) * P_ILAYER, (l + 2) * P_ILAYER - ((F.G == 256) ? (l == 0 ? 768 : 1792) : 0), (int)blockIdx.x, mfirst); if (l == 0) p_state_copies_tail(F, args, (int)blockIdx.x, mfirst); } }
;                   else { p_convert_tail(F, args, (l + 1) * P_ILAYER, (l + 2) * P_ILAYER - ((F.G == 256) ? (l == 0 ? 768 : 1792) : 0), (int)blockIdx.x, F.G); if (l == 0) p_state_copies_tail(F, args, (int)blockIdx.x, F.G); } } } }
.LBB0_1627:
	s_and_b64 vcc, exec, s[10:11]
	s_cbranch_vccz .LBB0_1707
	v_readlane_b32 s0, v254, 27
	s_cmp_ge_i32 s0, s28
	v_readlane_b32 s1, v254, 28
	s_cbranch_scc1 .LBB0_1707
	v_readlane_b32 s0, v255, 62
	v_readlane_b32 s1, v255, 63
	s_mul_i32 s2, s0, 0x1880
	v_readlane_b32 s0, v255, 53
	v_readlane_b32 s1, v255, 54
	s_and_b64 s[0:1], s[0:1], exec
	s_movk_i32 s0, 0xfb00
	s_cselect_b32 s7, s0, 0xfffff100
	v_readlane_b32 s0, v252, 62
	v_readlane_b32 s1, v252, 63
	s_and_b64 s[0:1], s[0:1], exec
	s_cselect_b32 s0, s7, 0
	s_add_i32 s7, s2, s0
	v_readlane_b32 s0, v253, 60
	s_addk_i32 s7, 0x3100
	v_mbcnt_lo_u32_b32 v0, -1, 0
	v_mbcnt_hi_u32_b32 v0, -1, v0
	s_add_i32 s29, s0, s2
	v_add_u32_e32 v0, s75, v0
	s_cmp_ge_i32 s29, s7
	s_cbranch_scc1 .LBB0_1682
	s_mul_hi_i32 s0, s29, 0x5397829d
	s_lshr_b32 s1, s0, 31
	s_ashr_i32 s0, s0, 11
	s_add_i32 s26, s0, s1
	s_mul_i32 s1, s26, 0x1880
	s_ashr_i32 s30, s26, 1
	s_and_b32 s0, s26, 1
	s_sub_i32 s1, s29, s1
	s_ashr_i32 s27, s26, 31
	s_mul_i32 s10, s26, 0x1880000
	v_readlane_b32 s11, v253, 5
	s_mul_hi_i32 s2, s26, 0x1880000
	s_add_u32 s22, s11, s10
	v_readlane_b32 s10, v253, 6
	s_addc_u32 s23, s10, s2
	s_mul_i32 s10, s26, 0x11000
	v_readlane_b32 s11, v253, 7
	s_mul_hi_i32 s2, s26, 0x11000
	s_add_u32 s24, s11, s10
	v_readlane_b32 s10, v253, 8
	s_addc_u32 s25, s10, s2
	v_readlane_b32 s48, v250, 0
	s_cmpk_gt_i32 s1, 0x5ff
	s_mov_b64 s[46:47], -1
	v_readlane_b32 s49, v250, 1
	s_cbranch_scc0 .LBB0_1639
	s_cmpk_gt_u32 s1, 0x7ff
	s_cbranch_scc0 .LBB0_1636
	s_mov_b64 s[18:19], -1
	s_cmpk_gt_u32 s1, 0x12ff
	s_mul_hi_i32 s2, s26, 0xb00000
	s_mul_i32 s13, s26, 0xb00000
	s_cbranch_scc0 .LBB0_1634
	v_readlane_b32 s56, v253, 26
	v_readlane_b32 s57, v253, 27
	s_add_u32 s10, s56, s13
	s_addc_u32 s11, s57, s2
	s_add_u32 s14, s22, 0x1300000
	s_addc_u32 s15, s23, 0
	s_lshl_b32 s16, s1, 1
	s_lshl_b32 s12, s1, 5
	s_and_b32 s16, s16, 0x7fffffc0
	v_readlane_b32 s58, v253, 28
	v_readlane_b32 s59, v253, 29
	v_readlane_b32 s60, v253, 30
	v_readlane_b32 s61, v253, 31
	v_readlane_b32 s62, v253, 32
	v_readlane_b32 s63, v253, 33
	s_and_b32 s12, s12, 0x3e0
	s_addk_i32 s16, 0xda00
	s_mov_b64 s[18:19], 0
